# P2: one static s_setprio 1 for waves 4-7 at phase entry (reset at phase exit)
# baseline (speedup 1.0000x reference)
; #define GAS __attribute__((address_space(1)))
; __device__ __forceinline__ int lane_id() { return (int)__builtin_amdgcn_mbcnt_hi(~0u, __builtin_amdgcn_mbcnt_lo(~0u, 0u)); }
; __device__ __forceinline__ const float* ld_uptr(const unsigned char* tblbase, int k) {
;     const unsigned long long v = *(const GAS unsigned long long*)(tblbase + 8 * k);
;     const unsigned lo = __builtin_amdgcn_readfirstlane((unsigned)v), hi = __builtin_amdgcn_readfirstlane((unsigned)(v >> 32));
;     return (const float*)(((unsigned long long)hi << 32) | lo);
; }
; __global__ void __launch_bounds__(NWAVES * 64, 2) fwd(Args args) {
;     ...
;     if (IN(2)) {
;         unsigned char* wsp = ws; asm volatile("" : "+s"(wsp)); const unsigned char* tbl = wsp + WS_PTRS;
;         const float* ret_gn = ld_uptr(tbl, 4); const float* diff_qn = ld_uptr(tbl, 5); const float* diff_kn = ld_uptr(tbl, 6); const float* lq1 = ld_uptr(tbl, 7); const float* lk1 = ld_uptr(tbl, 8);
;         const float* lq2 = ld_uptr(tbl, 9); const float* lk2 = ld_uptr(tbl, 10); const float* subln = ld_uptr(tbl, 11);
;         bf16_t* Z = (bf16_t*)(wsp + WS_Z); bf16_t* MIX = (bf16_t*)(wsp + WS_MIX);
;         int lane2 = lane_id(); asm volatile("" : "+v"(lane2));
;         const float d1 = wave_sum(lq1[lane2] * lk1[lane2]), d2 = wave_sum(lq2[lane2] * lk2[lane2]);
;         float lam; { float lv = __expf(d1) - __expf(d2) + 0.2f; asm volatile("" : "+v"(lv)); lam = __uint_as_float(__builtin_amdgcn_readfirstlane(__float_as_uint(lv))); }
;         const float mq = wave_max(fabsf(diff_qn[lane2])), mk = wave_max(fabsf(diff_kn[lane2]));
;         float shift; { float sv = 11.541560327111707f * mq * mk; asm volatile("" : "+v"(sv)); shift = __uint_as_float(__builtin_amdgcn_readfirstlane(__float_as_uint(sv))); }
.LBB0_561:
	s_cmp_lt_i32 s82, 3
	s_cselect_b64 s[2:3], -1, 0
	v_writelane_b32 v254, s2, 2
	s_and_b64 s[0:1], s[2:3], s[0:1]
	s_andn2_b64 vcc, exec, s[0:1]
	v_writelane_b32 v254, s3, 3
	s_cbranch_vccnz .LBB0_654
	v_writelane_b32 v254, s96, 4
	v_mov_b32_e32 v181, 0
	v_mbcnt_lo_u32_b32 v13, -1, 0
	v_writelane_b32 v254, s97, 5
	v_writelane_b32 v254, s94, 6
	v_writelane_b32 v254, s93, 7
	v_writelane_b32 v254, s92, 8
	s_cmpk_lt_u32 s92, 0x100
	s_cbranch_scc1 .Lp2_prio_done
	s_setprio 1
.Lp2_prio_done:
	v_writelane_b32 v254, s90, 9
	v_mbcnt_hi_u32_b32 v183, -1, v13
	v_mov_b32_e32 v12, 0x20000
	v_writelane_b32 v254, s91, 10
	v_writelane_b32 v254, s87, 11
	v_writelane_b32 v254, s88, 12
	v_mov_b32_e32 v16, v183
	s_mov_b32 s27, 0
	v_writelane_b32 v254, s89, 13
	v_writelane_b32 v254, s86, 14
	v_writelane_b32 v254, s84, 15
	s_nop 1
	v_writelane_b32 v254, s85, 16
	v_writelane_b32 v254, s79, 17
	v_writelane_b32 v254, s77, 18
	v_writelane_b32 v254, s80, 19
	s_mov_b64 s[0:1], s[80:81]
	s_add_u32 s2, s0, 0x20020
	s_addc_u32 s3, s1, 0
	global_load_dwordx4 v[0:3], v181, s[2:3] offset:16
	global_load_dwordx4 v[4:7], v181, s[2:3] offset:32
	global_load_dwordx4 v[8:11], v181, s[2:3] offset:48
	v_writelane_b32 v254, s81, 20
	global_load_dwordx4 v[12:15], v12, s[0:1] offset:32
	v_writelane_b32 v254, s82, 21
	v_ashrrev_i32_e32 v17, 31, v16
	v_lshlrev_b64 v[16:17], 2, v[16:17]
	v_writelane_b32 v254, s83, 22
	s_cmpk_gt_i32 s95, 0xff
	s_waitcnt vmcnt(0)
	v_readfirstlane_b32 s3, v3
	v_readfirstlane_b32 s2, v2
	v_readfirstlane_b32 s5, v5
	v_readfirstlane_b32 s4, v4
	v_readfirstlane_b32 s7, v7
	v_readfirstlane_b32 s6, v6
	v_readfirstlane_b32 s9, v9
	v_readfirstlane_b32 s8, v8
	v_lshl_add_u64 v[2:3], s[2:3], 0, v[16:17]
	v_lshl_add_u64 v[4:5], s[4:5], 0, v[16:17]
	v_lshl_add_u64 v[6:7], s[6:7], 0, v[16:17]
	v_lshl_add_u64 v[8:9], s[8:9], 0, v[16:17]
	flat_load_dword v18, v[2:3]
	flat_load_dword v19, v[4:5]
	flat_load_dword v20, v[6:7]
	flat_load_dword v21, v[8:9]
	v_and_b32_e32 v2, 64, v183
	v_xor_b32_e32 v3, 1, v183
	v_add_u32_e32 v2, 64, v2
	v_cmp_lt_i32_e32 vcc, v3, v2
	v_xor_b32_e32 v4, 2, v183
	v_xor_b32_e32 v5, 4, v183
	v_cndmask_b32_e32 v3, v183, v3, vcc
	v_lshlrev_b32_e32 v9, 2, v3
	v_cmp_lt_i32_e32 vcc, v4, v2
	v_xor_b32_e32 v6, 8, v183
	v_xor_b32_e32 v7, 16, v183
	v_cndmask_b32_e32 v4, v183, v4, vcc
	v_lshlrev_b32_e32 v4, 2, v4
	v_cmp_lt_i32_e32 vcc, v5, v2
	v_xor_b32_e32 v8, 32, v183
	v_readfirstlane_b32 s5, v1
	v_cndmask_b32_e32 v5, v183, v5, vcc
	v_lshlrev_b32_e32 v5, 2, v5
	v_cmp_lt_i32_e32 vcc, v6, v2
	v_readfirstlane_b32 s3, v15
	v_readfirstlane_b32 s2, v14
	v_cndmask_b32_e32 v6, v183, v6, vcc
	v_lshlrev_b32_e32 v6, 2, v6
	v_cmp_lt_i32_e32 vcc, v7, v2
	v_readfirstlane_b32 s4, v0
	v_readfirstlane_b32 s85, v11
	v_cndmask_b32_e32 v7, v183, v7, vcc
	v_lshlrev_b32_e32 v7, 2, v7
	v_cmp_lt_i32_e32 vcc, v8, v2
	v_readfirstlane_b32 s84, v10
	s_waitcnt vmcnt(0) lgkmcnt(0)
	v_mul_f32_e32 v3, v18, v19
	ds_bpermute_b32 v3, v9, v3
	v_mul_f32_e32 v22, v20, v21
	ds_bpermute_b32 v22, v9, v22
	v_cndmask_b32_e32 v2, v183, v8, vcc
	v_lshlrev_b32_e32 v8, 2, v2
	s_waitcnt lgkmcnt(1)
	v_fmac_f32_e32 v3, v18, v19
	ds_bpermute_b32 v18, v4, v3
	s_waitcnt lgkmcnt(1)
	v_fmac_f32_e32 v22, v20, v21
	ds_bpermute_b32 v19, v4, v22
	s_waitcnt lgkmcnt(1)
	v_add_f32_e32 v3, v3, v18
	s_waitcnt lgkmcnt(0)
	v_add_f32_e32 v18, v22, v19
	ds_bpermute_b32 v19, v5, v3
	ds_bpermute_b32 v20, v5, v18
	s_waitcnt lgkmcnt(1)
	v_add_f32_e32 v3, v3, v19
	s_waitcnt lgkmcnt(0)
	v_add_f32_e32 v18, v18, v20
	ds_bpermute_b32 v19, v6, v3
	ds_bpermute_b32 v20, v6, v18
	s_waitcnt lgkmcnt(1)
	v_add_f32_e32 v3, v3, v19
	s_waitcnt lgkmcnt(0)
	v_add_f32_e32 v18, v18, v20
	ds_bpermute_b32 v19, v7, v3
	ds_bpermute_b32 v20, v7, v18
	s_waitcnt lgkmcnt(1)
	v_add_f32_e32 v2, v3, v19
	s_waitcnt lgkmcnt(0)
	v_add_f32_e32 v3, v18, v20
	ds_bpermute_b32 v18, v8, v2
	ds_bpermute_b32 v19, v8, v3
	s_waitcnt lgkmcnt(1)
	v_add_f32_e32 v1, v2, v18
	s_waitcnt lgkmcnt(0)
	v_add_f32_e32 v2, v3, v19
	v_mul_f32_e32 v1, 0x3fb8aa3b, v1
	v_mul_f32_e32 v2, 0x3fb8aa3b, v2
	v_exp_f32_e32 v14, v1
	v_exp_f32_e32 v15, v2
	v_lshl_add_u64 v[0:1], s[2:3], 0, v[16:17]
	v_lshl_add_u64 v[2:3], s[4:5], 0, v[16:17]
	v_readfirstlane_b32 s2, v13
	v_sub_f32_e32 v14, v14, v15
	v_add_f32_e32 v14, 0x3e4ccccd, v14
	flat_load_dword v15, v[0:1]
	flat_load_dword v16, v[2:3]
	v_writelane_b32 v254, s2, 23
	v_readfirstlane_b32 s2, v12
	v_readfirstlane_b32 s28, v14
	s_waitcnt vmcnt(0) lgkmcnt(0)
	v_and_b32_e32 v0, 0x7fffffff, v15
	v_and_b32_e32 v1, 0x7fffffff, v16
	ds_bpermute_b32 v0, v9, v0
	ds_bpermute_b32 v1, v9, v1
	v_max_f32_e64 v2, |v15|, |v15|
	v_max_f32_e64 v3, |v16|, |v16|
	v_writelane_b32 v254, s2, 24
	s_waitcnt lgkmcnt(1)
	v_max_f32_e32 v0, v0, v0
	s_waitcnt lgkmcnt(0)
	v_max_f32_e32 v1, v1, v1
	v_max_f32_e32 v0, v2, v0
	v_max_f32_e32 v1, v3, v1
	ds_bpermute_b32 v2, v4, v0
	ds_bpermute_b32 v3, v4, v1
	s_waitcnt lgkmcnt(1)
	v_max_f32_e32 v2, v2, v2
	s_waitcnt lgkmcnt(0)
	v_max_f32_e32 v3, v3, v3
	v_max_f32_e32 v0, v0, v2
	v_max_f32_e32 v1, v1, v3
	ds_bpermute_b32 v2, v5, v0
	ds_bpermute_b32 v3, v5, v1
	s_waitcnt lgkmcnt(1)
	v_max_f32_e32 v2, v2, v2
	s_waitcnt lgkmcnt(0)
	v_max_f32_e32 v3, v3, v3
	v_max_f32_e32 v0, v0, v2
	v_max_f32_e32 v1, v1, v3
	ds_bpermute_b32 v2, v6, v0
	ds_bpermute_b32 v3, v6, v1
	s_waitcnt lgkmcnt(1)
	v_max_f32_e32 v2, v2, v2
	s_waitcnt lgkmcnt(0)
	v_max_f32_e32 v3, v3, v3
	v_max_f32_e32 v0, v0, v2
	v_max_f32_e32 v1, v1, v3
	ds_bpermute_b32 v2, v7, v0
	ds_bpermute_b32 v3, v7, v1
	s_waitcnt lgkmcnt(1)
	v_max_f32_e32 v2, v2, v2
	s_waitcnt lgkmcnt(0)
	v_max_f32_e32 v3, v3, v3
	v_max_f32_e32 v0, v0, v2
	v_max_f32_e32 v1, v1, v3
	ds_bpermute_b32 v2, v8, v0
	ds_bpermute_b32 v3, v8, v1
	s_waitcnt lgkmcnt(1)
	v_max_f32_e32 v2, v2, v2
	s_waitcnt lgkmcnt(0)
	v_max_f32_e32 v3, v3, v3
	v_max_f32_e32 v0, v0, v2
	v_max_f32_e32 v1, v1, v3
	v_mul_f32_e32 v0, 0x4138aa3b, v0
	v_mul_f32_e32 v0, v0, v1
	s_nop 0
	v_readfirstlane_b32 s2, v0
	s_cbranch_scc1 .LBB0_653
; __global__ void __launch_bounds__(NWAVES * 64, 2) fwd(Args args) {
;     ...
;         for (int pi = vcu; pi < 256; pi += G) {
;             const int bh = pi >> 3, tp = pi & 7, b = bh >> 3, h = bh & 7;
;             attn_item<true>(lds, Z, MIX, b, h, 15 - tp, lam, shift, subln, 0, wid, 0);
	s_add_u32 s30, s0, 0x5300000
	s_addc_u32 s31, s1, 0
	s_add_u32 s88, s0, 0x2f00000
	s_addc_u32 s89, s1, 0
	s_lshl_b32 s29, s60, 4
	s_lshl_b32 s34, s60, 3
	s_lshl_b32 s35, s60, 2
	s_add_i32 s90, s33, 0
	v_sub_f32_e64 v0, 0, s2
	s_add_u32 s2, s0, 0x54c2800
	v_writelane_b32 v254, s2, 25
	s_addc_u32 s2, s1, 0
	v_writelane_b32 v254, s2, 26
	s_lshl_b32 s2, s95, 5
	s_lshl_b32 s3, s78, 5
	v_writelane_b32 v254, s3, 27
	s_add_u32 s3, s0, 0x54c0800
	v_writelane_b32 v254, s3, 28
	s_addc_u32 s3, s1, 0
	v_writelane_b32 v254, s3, 29
	s_add_u32 s0, s0, 0x54c0400
	v_writelane_b32 v254, s0, 30
	s_addc_u32 s0, s1, 0
	v_writelane_b32 v254, s0, 31
	v_writelane_b32 v254, s78, 32
	v_writelane_b32 v254, s66, 33
	v_writelane_b32 v254, s84, 34
	s_add_i32 s17, s90, 0x2000
	s_add_i32 s38, s90, 0x6000
	v_writelane_b32 v254, s85, 35
	v_writelane_b32 v254, s28, 36
	v_writelane_b32 v254, s30, 37
	s_add_i32 s39, s90, 0x8000
	s_add_i32 s18, s90, 0xa000
	v_writelane_b32 v254, s31, 38
	v_writelane_b32 v254, s88, 39
	s_add_i32 s40, s90, 0xc000
	s_add_i32 s41, s90, 0xe000
	v_writelane_b32 v254, s89, 40
	v_writelane_b32 v254, s29, 41
	v_writelane_b32 v254, s34, 42
	v_writelane_b32 v254, s35, 43
	v_writelane_b32 v254, s17, 44
	v_writelane_b32 v254, s38, 45
	v_writelane_b32 v254, s39, 46
	v_writelane_b32 v254, s18, 47
	v_writelane_b32 v254, s40, 48
	s_add_i32 s43, s90, 0x4000
	v_writelane_b32 v254, s41, 49
	v_mov_b32_e32 v1, v0
	v_mov_b32_e32 v2, v0
	v_mov_b32_e32 v3, v0
	s_movk_i32 s36, 0x3800
	s_mov_b64 s[14:15], 0x1800
	s_movk_i32 s16, 0x1000
	s_movk_i32 s37, 0x1c00
	s_mov_b64 s[96:97], 0x80
	s_movk_i32 s67, 0xe0
	s_movk_i32 s73, 0x60
	s_movk_i32 s74, 0x80
	s_movk_i32 s75, 0xa0
	s_movk_i32 s79, 0xc0
	s_mov_b64 s[92:93], 0x3000
	s_mov_b32 s42, 0x800000
	v_mov_b32_e32 v186, 0xe0
	s_mov_b32 s44, s95
	s_mov_b32 s101, 0
	s_mov_b32 s98, 0
	s_mov_b32 s99, 0x89abcdef
	v_writelane_b32 v254, s43, 50
	s_branch .LBB0_565

; __global__ void __launch_bounds__(NWAVES * 64, 2) fwd(Args args) {
;     ...
;         __syncthreads();
;     }
.LBB0_653:
	v_readlane_b32 s80, v254, 19
	v_readlane_b32 s84, v254, 15
	v_readlane_b32 s88, v254, 12
	v_readlane_b32 s90, v254, 9
	v_readlane_b32 s96, v254, 4
	v_readlane_b32 s77, v254, 18
	v_readlane_b32 s81, v254, 20
	v_readlane_b32 s82, v254, 21
	v_readlane_b32 s83, v254, 22
	v_readlane_b32 s79, v254, 17
	v_readlane_b32 s85, v254, 16
	v_readlane_b32 s86, v254, 14
	v_readlane_b32 s89, v254, 13
	v_readlane_b32 s87, v254, 11
	v_readlane_b32 s91, v254, 10
	v_readlane_b32 s92, v254, 8
	v_readlane_b32 s93, v254, 7
	v_readlane_b32 s94, v254, 6
	v_readlane_b32 s97, v254, 5
	s_setprio 0
	s_waitcnt lgkmcnt(0)
	s_barrier
